# P1 rotary epilogue rewritten by hand: cos/sin table loads of 3 row-steps kept in flight in spare K-loop fragment registers with counted vmcnt (was 8 serial load-wait-store round trips)
# speedup vs baseline: 1.0071x; 1.0010x over previous
.LBB0_204:
	v_lshlrev_b64 v[132:133], 1, v[154:155]
	v_mov_b64_e32 v[128:129], s[20:21]
	v_lshlrev_b32_e32 v154, 7, v190
	v_and_b32_e32 v154, 0x7ff80, v154
	v_lshl_add_u64 v[172:173], v[158:159], 0, v[154:155]
	v_lshl_add_u64 v[200:201], v[156:157], 0, v[154:155]
	global_load_dwordx4 v[202:205], v[172:173], off
	global_load_dwordx4 v[206:209], v[172:173], off offset:16
	global_load_dwordx4 v[210:213], v[200:201], off
	global_load_dwordx4 v[214:217], v[200:201], off offset:16
	v_add_u32_e32 v131, 0x10, v190
	v_lshlrev_b32_e32 v154, 7, v131
	v_and_b32_e32 v154, 0x7ff80, v154
	v_lshl_add_u64 v[172:173], v[158:159], 0, v[154:155]
	v_lshl_add_u64 v[200:201], v[156:157], 0, v[154:155]
	global_load_dwordx4 v[218:221], v[172:173], off
	global_load_dwordx4 v[226:229], v[172:173], off offset:16
	global_load_dwordx4 v[230:233], v[200:201], off
	global_load_dwordx4 v[234:237], v[200:201], off offset:16
	v_add_u32_e32 v131, 0x20, v190
	v_lshlrev_b32_e32 v154, 7, v131
	v_and_b32_e32 v154, 0x7ff80, v154
	v_lshl_add_u64 v[172:173], v[158:159], 0, v[154:155]
	v_lshl_add_u64 v[200:201], v[156:157], 0, v[154:155]
	global_load_dwordx4 v[238:241], v[172:173], off
	global_load_dwordx4 v[242:245], v[172:173], off offset:16
	global_load_dwordx4 v[134:137], v[200:201], off
	global_load_dwordx4 v[138:141], v[200:201], off offset:16
	v_mad_i64_i32 v[142:143], s[52:53], v190, s87, v[128:129]
	v_lshl_add_u64 v[142:143], v[142:143], 0, v[132:133]
	s_waitcnt vmcnt(8)
	v_pk_mul_f32 v[192:193], v[118:119], v[204:205]
	v_pk_mul_f32 v[194:195], v[116:117], v[202:203]
	v_pk_mul_f32 v[196:197], v[114:115], v[208:209]
	v_pk_mul_f32 v[198:199], v[112:113], v[206:207]
	v_pk_mul_f32 v[204:205], v[126:127], v[204:205]
	v_pk_mul_f32 v[202:203], v[124:125], v[202:203]
	v_pk_mul_f32 v[208:209], v[122:123], v[208:209]
	v_pk_mul_f32 v[206:207], v[120:121], v[206:207]
	v_pk_fma_f32 v[126:127], v[126:127], v[212:213], v[192:193] neg_lo:[0,0,1] neg_hi:[0,0,1]
	v_pk_fma_f32 v[124:125], v[124:125], v[210:211], v[194:195] neg_lo:[0,0,1] neg_hi:[0,0,1]
	v_pk_fma_f32 v[122:123], v[122:123], v[216:217], v[196:197] neg_lo:[0,0,1] neg_hi:[0,0,1]
	v_pk_fma_f32 v[120:121], v[120:121], v[214:215], v[198:199] neg_lo:[0,0,1] neg_hi:[0,0,1]
	v_pk_fma_f32 v[118:119], v[118:119], v[212:213], v[204:205]
	v_pk_fma_f32 v[116:117], v[116:117], v[210:211], v[202:203]
	v_pk_fma_f32 v[202:203], v[114:115], v[216:217], v[208:209]
	v_pk_fma_f32 v[204:205], v[112:113], v[214:215], v[206:207]
	v_cvt_pk_bf16_f32 v112, v124, v125
	v_cvt_pk_bf16_f32 v113, v126, v127
	v_cvt_pk_bf16_f32 v114, v120, v121
	v_cvt_pk_bf16_f32 v115, v122, v123
	v_cvt_pk_bf16_f32 v116, v116, v117
	v_cvt_pk_bf16_f32 v117, v118, v119
	v_cvt_pk_bf16_f32 v118, v204, v205
	v_cvt_pk_bf16_f32 v119, v202, v203
	global_store_dwordx4 v[142:143], v[112:115], off
	global_store_dwordx4 v[142:143], v[116:119], off offset:64
	v_add_u32_e32 v131, 0x30, v190
	v_lshlrev_b32_e32 v154, 7, v131
	v_and_b32_e32 v154, 0x7ff80, v154
	v_lshl_add_u64 v[172:173], v[158:159], 0, v[154:155]
	v_lshl_add_u64 v[200:201], v[156:157], 0, v[154:155]
	global_load_dwordx4 v[202:205], v[172:173], off
	global_load_dwordx4 v[206:209], v[172:173], off offset:16
	global_load_dwordx4 v[210:213], v[200:201], off
	global_load_dwordx4 v[214:217], v[200:201], off offset:16
	v_add_u32_e32 v130, 0x10, v190
	v_mad_i64_i32 v[142:143], s[52:53], v130, s87, v[128:129]
	v_lshl_add_u64 v[142:143], v[142:143], 0, v[132:133]
	s_waitcnt vmcnt(10)
	v_pk_mul_f32 v[192:193], v[102:103], v[220:221]
	v_pk_mul_f32 v[194:195], v[100:101], v[218:219]
	v_pk_mul_f32 v[196:197], v[98:99], v[228:229]
	v_pk_mul_f32 v[198:199], v[96:97], v[226:227]
	v_pk_mul_f32 v[220:221], v[110:111], v[220:221]
	v_pk_mul_f32 v[218:219], v[108:109], v[218:219]
	v_pk_mul_f32 v[228:229], v[106:107], v[228:229]
	v_pk_mul_f32 v[226:227], v[104:105], v[226:227]
	v_pk_fma_f32 v[110:111], v[110:111], v[232:233], v[192:193] neg_lo:[0,0,1] neg_hi:[0,0,1]
	v_pk_fma_f32 v[108:109], v[108:109], v[230:231], v[194:195] neg_lo:[0,0,1] neg_hi:[0,0,1]
	v_pk_fma_f32 v[106:107], v[106:107], v[236:237], v[196:197] neg_lo:[0,0,1] neg_hi:[0,0,1]
	v_pk_fma_f32 v[104:105], v[104:105], v[234:235], v[198:199] neg_lo:[0,0,1] neg_hi:[0,0,1]
	v_pk_fma_f32 v[102:103], v[102:103], v[232:233], v[220:221]
	v_pk_fma_f32 v[100:101], v[100:101], v[230:231], v[218:219]
	v_pk_fma_f32 v[218:219], v[98:99], v[236:237], v[228:229]
	v_pk_fma_f32 v[220:221], v[96:97], v[234:235], v[226:227]
	v_cvt_pk_bf16_f32 v96, v108, v109
	v_cvt_pk_bf16_f32 v97, v110, v111
	v_cvt_pk_bf16_f32 v98, v104, v105
	v_cvt_pk_bf16_f32 v99, v106, v107
	v_cvt_pk_bf16_f32 v100, v100, v101
	v_cvt_pk_bf16_f32 v101, v102, v103
	v_cvt_pk_bf16_f32 v102, v220, v221
	v_cvt_pk_bf16_f32 v103, v218, v219
	global_store_dwordx4 v[142:143], v[96:99], off
	global_store_dwordx4 v[142:143], v[100:103], off offset:64
	v_add_u32_e32 v131, 0x80, v190
	v_lshlrev_b32_e32 v154, 7, v131
	v_and_b32_e32 v154, 0x7ff80, v154
	v_lshl_add_u64 v[172:173], v[158:159], 0, v[154:155]
	v_lshl_add_u64 v[200:201], v[156:157], 0, v[154:155]
	global_load_dwordx4 v[218:221], v[172:173], off
	global_load_dwordx4 v[226:229], v[172:173], off offset:16
	global_load_dwordx4 v[230:233], v[200:201], off
	global_load_dwordx4 v[234:237], v[200:201], off offset:16
	v_add_u32_e32 v130, 0x20, v190
	v_mad_i64_i32 v[142:143], s[52:53], v130, s87, v[128:129]
	v_lshl_add_u64 v[142:143], v[142:143], 0, v[132:133]
	s_waitcnt vmcnt(12)
	v_pk_mul_f32 v[192:193], v[86:87], v[240:241]
	v_pk_mul_f32 v[194:195], v[84:85], v[238:239]
	v_pk_mul_f32 v[196:197], v[82:83], v[244:245]
	v_pk_mul_f32 v[198:199], v[80:81], v[242:243]
	v_pk_mul_f32 v[240:241], v[94:95], v[240:241]
	v_pk_mul_f32 v[238:239], v[92:93], v[238:239]
	v_pk_mul_f32 v[244:245], v[90:91], v[244:245]
	v_pk_mul_f32 v[242:243], v[88:89], v[242:243]
	v_pk_fma_f32 v[94:95], v[94:95], v[136:137], v[192:193] neg_lo:[0,0,1] neg_hi:[0,0,1]
	v_pk_fma_f32 v[92:93], v[92:93], v[134:135], v[194:195] neg_lo:[0,0,1] neg_hi:[0,0,1]
	v_pk_fma_f32 v[90:91], v[90:91], v[140:141], v[196:197] neg_lo:[0,0,1] neg_hi:[0,0,1]
	v_pk_fma_f32 v[88:89], v[88:89], v[138:139], v[198:199] neg_lo:[0,0,1] neg_hi:[0,0,1]
	v_pk_fma_f32 v[86:87], v[86:87], v[136:137], v[240:241]
	v_pk_fma_f32 v[84:85], v[84:85], v[134:135], v[238:239]
	v_pk_fma_f32 v[238:239], v[82:83], v[140:141], v[244:245]
	v_pk_fma_f32 v[240:241], v[80:81], v[138:139], v[242:243]
	v_cvt_pk_bf16_f32 v80, v92, v93
	v_cvt_pk_bf16_f32 v81, v94, v95
	v_cvt_pk_bf16_f32 v82, v88, v89
	v_cvt_pk_bf16_f32 v83, v90, v91
	v_cvt_pk_bf16_f32 v84, v84, v85
	v_cvt_pk_bf16_f32 v85, v86, v87
	v_cvt_pk_bf16_f32 v86, v240, v241
	v_cvt_pk_bf16_f32 v87, v238, v239
	global_store_dwordx4 v[142:143], v[80:83], off
	global_store_dwordx4 v[142:143], v[84:87], off offset:64
	v_add_u32_e32 v131, 0x90, v190
	v_lshlrev_b32_e32 v154, 7, v131
	v_and_b32_e32 v154, 0x7ff80, v154
	v_lshl_add_u64 v[172:173], v[158:159], 0, v[154:155]
	v_lshl_add_u64 v[200:201], v[156:157], 0, v[154:155]
	global_load_dwordx4 v[238:241], v[172:173], off
	global_load_dwordx4 v[242:245], v[172:173], off offset:16
	global_load_dwordx4 v[134:137], v[200:201], off
	global_load_dwordx4 v[138:141], v[200:201], off offset:16
	v_add_u32_e32 v130, 0x30, v190
	v_mad_i64_i32 v[142:143], s[52:53], v130, s87, v[128:129]
	v_lshl_add_u64 v[142:143], v[142:143], 0, v[132:133]
	s_waitcnt vmcnt(12)
	v_pk_mul_f32 v[192:193], v[70:71], v[204:205]
	v_pk_mul_f32 v[194:195], v[68:69], v[202:203]
	v_pk_mul_f32 v[196:197], v[66:67], v[208:209]
	v_pk_mul_f32 v[198:199], v[64:65], v[206:207]
	v_pk_mul_f32 v[204:205], v[78:79], v[204:205]
	v_pk_mul_f32 v[202:203], v[76:77], v[202:203]
	v_pk_mul_f32 v[208:209], v[74:75], v[208:209]
	v_pk_mul_f32 v[206:207], v[72:73], v[206:207]
	v_pk_fma_f32 v[78:79], v[78:79], v[212:213], v[192:193] neg_lo:[0,0,1] neg_hi:[0,0,1]
	v_pk_fma_f32 v[76:77], v[76:77], v[210:211], v[194:195] neg_lo:[0,0,1] neg_hi:[0,0,1]
	v_pk_fma_f32 v[74:75], v[74:75], v[216:217], v[196:197] neg_lo:[0,0,1] neg_hi:[0,0,1]
	v_pk_fma_f32 v[72:73], v[72:73], v[214:215], v[198:199] neg_lo:[0,0,1] neg_hi:[0,0,1]
	v_pk_fma_f32 v[70:71], v[70:71], v[212:213], v[204:205]
	v_pk_fma_f32 v[68:69], v[68:69], v[210:211], v[202:203]
	v_pk_fma_f32 v[202:203], v[66:67], v[216:217], v[208:209]
	v_pk_fma_f32 v[204:205], v[64:65], v[214:215], v[206:207]
	v_cvt_pk_bf16_f32 v64, v76, v77
	v_cvt_pk_bf16_f32 v65, v78, v79
	v_cvt_pk_bf16_f32 v66, v72, v73
	v_cvt_pk_bf16_f32 v67, v74, v75
	v_cvt_pk_bf16_f32 v68, v68, v69
	v_cvt_pk_bf16_f32 v69, v70, v71
	v_cvt_pk_bf16_f32 v70, v204, v205
	v_cvt_pk_bf16_f32 v71, v202, v203
	global_store_dwordx4 v[142:143], v[64:67], off
	global_store_dwordx4 v[142:143], v[68:71], off offset:64
	v_add_u32_e32 v131, 0xa0, v190
	v_lshlrev_b32_e32 v154, 7, v131
	v_and_b32_e32 v154, 0x7ff80, v154
	v_lshl_add_u64 v[172:173], v[158:159], 0, v[154:155]
	v_lshl_add_u64 v[200:201], v[156:157], 0, v[154:155]
	global_load_dwordx4 v[202:205], v[172:173], off
	global_load_dwordx4 v[206:209], v[172:173], off offset:16
	global_load_dwordx4 v[210:213], v[200:201], off
	global_load_dwordx4 v[214:217], v[200:201], off offset:16
	v_add_u32_e32 v130, 0x80, v190
	v_mad_i64_i32 v[142:143], s[52:53], v130, s87, v[128:129]
	v_lshl_add_u64 v[142:143], v[142:143], 0, v[132:133]
	s_waitcnt vmcnt(12)
	v_pk_mul_f32 v[192:193], v[54:55], v[220:221]
	v_pk_mul_f32 v[194:195], v[52:53], v[218:219]
	v_pk_mul_f32 v[196:197], v[50:51], v[228:229]
	v_pk_mul_f32 v[198:199], v[48:49], v[226:227]
	v_pk_mul_f32 v[220:221], v[62:63], v[220:221]
	v_pk_mul_f32 v[218:219], v[60:61], v[218:219]
	v_pk_mul_f32 v[228:229], v[58:59], v[228:229]
	v_pk_mul_f32 v[226:227], v[56:57], v[226:227]
	v_pk_fma_f32 v[62:63], v[62:63], v[232:233], v[192:193] neg_lo:[0,0,1] neg_hi:[0,0,1]
	v_pk_fma_f32 v[60:61], v[60:61], v[230:231], v[194:195] neg_lo:[0,0,1] neg_hi:[0,0,1]
	v_pk_fma_f32 v[58:59], v[58:59], v[236:237], v[196:197] neg_lo:[0,0,1] neg_hi:[0,0,1]
	v_pk_fma_f32 v[56:57], v[56:57], v[234:235], v[198:199] neg_lo:[0,0,1] neg_hi:[0,0,1]
	v_pk_fma_f32 v[54:55], v[54:55], v[232:233], v[220:221]
	v_pk_fma_f32 v[52:53], v[52:53], v[230:231], v[218:219]
	v_pk_fma_f32 v[218:219], v[50:51], v[236:237], v[228:229]
	v_pk_fma_f32 v[220:221], v[48:49], v[234:235], v[226:227]
	v_cvt_pk_bf16_f32 v48, v60, v61
	v_cvt_pk_bf16_f32 v49, v62, v63
	v_cvt_pk_bf16_f32 v50, v56, v57
	v_cvt_pk_bf16_f32 v51, v58, v59
	v_cvt_pk_bf16_f32 v52, v52, v53
	v_cvt_pk_bf16_f32 v53, v54, v55
	v_cvt_pk_bf16_f32 v54, v220, v221
	v_cvt_pk_bf16_f32 v55, v218, v219
	global_store_dwordx4 v[142:143], v[48:51], off
	global_store_dwordx4 v[142:143], v[52:55], off offset:64
	v_add_u32_e32 v131, 0xb0, v190
	v_lshlrev_b32_e32 v154, 7, v131
	v_and_b32_e32 v154, 0x7ff80, v154
	v_lshl_add_u64 v[172:173], v[158:159], 0, v[154:155]
	v_lshl_add_u64 v[200:201], v[156:157], 0, v[154:155]
	global_load_dwordx4 v[218:221], v[172:173], off
	global_load_dwordx4 v[226:229], v[172:173], off offset:16
	global_load_dwordx4 v[230:233], v[200:201], off
	global_load_dwordx4 v[234:237], v[200:201], off offset:16
	v_add_u32_e32 v130, 0x90, v190
	v_mad_i64_i32 v[142:143], s[52:53], v130, s87, v[128:129]
	v_lshl_add_u64 v[142:143], v[142:143], 0, v[132:133]
	s_waitcnt vmcnt(12)
	v_pk_mul_f32 v[192:193], v[38:39], v[240:241]
	v_pk_mul_f32 v[194:195], v[36:37], v[238:239]
	v_pk_mul_f32 v[196:197], v[34:35], v[244:245]
	v_pk_mul_f32 v[198:199], v[32:33], v[242:243]
	v_pk_mul_f32 v[240:241], v[46:47], v[240:241]
	v_pk_mul_f32 v[238:239], v[44:45], v[238:239]
	v_pk_mul_f32 v[244:245], v[42:43], v[244:245]
	v_pk_mul_f32 v[242:243], v[40:41], v[242:243]
	v_pk_fma_f32 v[46:47], v[46:47], v[136:137], v[192:193] neg_lo:[0,0,1] neg_hi:[0,0,1]
	v_pk_fma_f32 v[44:45], v[44:45], v[134:135], v[194:195] neg_lo:[0,0,1] neg_hi:[0,0,1]
	v_pk_fma_f32 v[42:43], v[42:43], v[140:141], v[196:197] neg_lo:[0,0,1] neg_hi:[0,0,1]
	v_pk_fma_f32 v[40:41], v[40:41], v[138:139], v[198:199] neg_lo:[0,0,1] neg_hi:[0,0,1]
	v_pk_fma_f32 v[38:39], v[38:39], v[136:137], v[240:241]
	v_pk_fma_f32 v[36:37], v[36:37], v[134:135], v[238:239]
	v_pk_fma_f32 v[238:239], v[34:35], v[140:141], v[244:245]
	v_pk_fma_f32 v[240:241], v[32:33], v[138:139], v[242:243]
	v_cvt_pk_bf16_f32 v32, v44, v45
	v_cvt_pk_bf16_f32 v33, v46, v47
	v_cvt_pk_bf16_f32 v34, v40, v41
	v_cvt_pk_bf16_f32 v35, v42, v43
	v_cvt_pk_bf16_f32 v36, v36, v37
	v_cvt_pk_bf16_f32 v37, v38, v39
	v_cvt_pk_bf16_f32 v38, v240, v241
	v_cvt_pk_bf16_f32 v39, v238, v239
	global_store_dwordx4 v[142:143], v[32:35], off
	global_store_dwordx4 v[142:143], v[36:39], off offset:64
	v_add_u32_e32 v130, 0xa0, v190
	v_mad_i64_i32 v[142:143], s[52:53], v130, s87, v[128:129]
	v_lshl_add_u64 v[142:143], v[142:143], 0, v[132:133]
	s_waitcnt vmcnt(8)
	v_pk_mul_f32 v[192:193], v[22:23], v[204:205]
	v_pk_mul_f32 v[194:195], v[20:21], v[202:203]
	v_pk_mul_f32 v[196:197], v[18:19], v[208:209]
	v_pk_mul_f32 v[198:199], v[16:17], v[206:207]
	v_pk_mul_f32 v[204:205], v[30:31], v[204:205]
	v_pk_mul_f32 v[202:203], v[28:29], v[202:203]
	v_pk_mul_f32 v[208:209], v[26:27], v[208:209]
	v_pk_mul_f32 v[206:207], v[24:25], v[206:207]
	v_pk_fma_f32 v[30:31], v[30:31], v[212:213], v[192:193] neg_lo:[0,0,1] neg_hi:[0,0,1]
	v_pk_fma_f32 v[28:29], v[28:29], v[210:211], v[194:195] neg_lo:[0,0,1] neg_hi:[0,0,1]
	v_pk_fma_f32 v[26:27], v[26:27], v[216:217], v[196:197] neg_lo:[0,0,1] neg_hi:[0,0,1]
	v_pk_fma_f32 v[24:25], v[24:25], v[214:215], v[198:199] neg_lo:[0,0,1] neg_hi:[0,0,1]
	v_pk_fma_f32 v[22:23], v[22:23], v[212:213], v[204:205]
	v_pk_fma_f32 v[20:21], v[20:21], v[210:211], v[202:203]
	v_pk_fma_f32 v[202:203], v[18:19], v[216:217], v[208:209]
	v_pk_fma_f32 v[204:205], v[16:17], v[214:215], v[206:207]
	v_cvt_pk_bf16_f32 v16, v28, v29
	v_cvt_pk_bf16_f32 v17, v30, v31
	v_cvt_pk_bf16_f32 v18, v24, v25
	v_cvt_pk_bf16_f32 v19, v26, v27
	v_cvt_pk_bf16_f32 v20, v20, v21
	v_cvt_pk_bf16_f32 v21, v22, v23
	v_cvt_pk_bf16_f32 v22, v204, v205
	v_cvt_pk_bf16_f32 v23, v202, v203
	global_store_dwordx4 v[142:143], v[16:19], off
	global_store_dwordx4 v[142:143], v[20:23], off offset:64
	v_add_u32_e32 v130, 0xb0, v190
	v_mad_i64_i32 v[142:143], s[52:53], v130, s87, v[128:129]
	v_lshl_add_u64 v[142:143], v[142:143], 0, v[132:133]
	s_waitcnt vmcnt(4)
	v_pk_mul_f32 v[192:193], v[6:7], v[220:221]
	v_pk_mul_f32 v[194:195], v[4:5], v[218:219]
	v_pk_mul_f32 v[196:197], v[2:3], v[228:229]
	v_pk_mul_f32 v[198:199], v[0:1], v[226:227]
	v_pk_mul_f32 v[220:221], v[14:15], v[220:221]
	v_pk_mul_f32 v[218:219], v[12:13], v[218:219]
	v_pk_mul_f32 v[228:229], v[10:11], v[228:229]
	v_pk_mul_f32 v[226:227], v[8:9], v[226:227]
	v_pk_fma_f32 v[14:15], v[14:15], v[232:233], v[192:193] neg_lo:[0,0,1] neg_hi:[0,0,1]
	v_pk_fma_f32 v[12:13], v[12:13], v[230:231], v[194:195] neg_lo:[0,0,1] neg_hi:[0,0,1]
	v_pk_fma_f32 v[10:11], v[10:11], v[236:237], v[196:197] neg_lo:[0,0,1] neg_hi:[0,0,1]
	v_pk_fma_f32 v[8:9], v[8:9], v[234:235], v[198:199] neg_lo:[0,0,1] neg_hi:[0,0,1]
	v_pk_fma_f32 v[6:7], v[6:7], v[232:233], v[220:221]
	v_pk_fma_f32 v[4:5], v[4:5], v[230:231], v[218:219]
	v_pk_fma_f32 v[218:219], v[2:3], v[236:237], v[228:229]
	v_pk_fma_f32 v[220:221], v[0:1], v[234:235], v[226:227]
	v_cvt_pk_bf16_f32 v0, v12, v13
	v_cvt_pk_bf16_f32 v1, v14, v15
	v_cvt_pk_bf16_f32 v2, v8, v9
	v_cvt_pk_bf16_f32 v3, v10, v11
	v_cvt_pk_bf16_f32 v4, v4, v5
	v_cvt_pk_bf16_f32 v5, v6, v7
	v_cvt_pk_bf16_f32 v6, v220, v221
	v_cvt_pk_bf16_f32 v7, v218, v219
	global_store_dwordx4 v[142:143], v[0:3], off
	global_store_dwordx4 v[142:143], v[4:7], off offset:64
	s_andn2_b64 vcc, exec, s[8:9]
	s_mov_b64 s[8:9], -1
	s_cbranch_vccnz .LBB0_189
